# swiglu epilogue rewritten (scalar f32 stage-ordered, lane-transposed coalesced stores); up-GEMM first K-iteration peeled with C=0; grid barrier gather with 4 loads in flight
# speedup vs baseline: 1.0026x; 1.0026x over previous
; __device__ __forceinline__ unsigned pk2(float lo, float hi) { return pg8::cvt_pk_bf16(lo, hi); }
; __device__ __forceinline__ float siluf_(float x) { return x * sigmoidf_(x); }
;     __device__ __forceinline__ void operator()(const f32x4 (&acc)[2][2][4][2], const pg8::Unit& u, int wr, int wc, int fr, int fq) const {
;         const int row0 = u.pm * 256 + wr * 64 + fr, col0 = u.pn * 128 + wc * 32 + 8 * fq;
; #pragma unroll
;         for (int ai = 0; ai < 2; ++ai)
; #pragma unroll
;             for (int m = 0; m < 4; ++m) {
;                 bf16_t* rowp = O + (size_t)(row0 + ai * 128 + m * 16) * ldc + col0;
;                 const f32x4 a0 = acc[ai][0][m][0], a1 = acc[ai][0][m][1], g0 = acc[ai][1][m][0], g1 = acc[ai][1][m][1];
;                 u32x4 w;
;                 w.x = pk2(siluf_(a0[0]) * g0[0], siluf_(a0[1]) * g0[1]); w.y = pk2(siluf_(a0[2]) * g0[2], siluf_(a0[3]) * g0[3]);
;                 w.z = pk2(siluf_(a1[0]) * g1[0], siluf_(a1[1]) * g1[1]); w.w = pk2(siluf_(a1[2]) * g1[2], siluf_(a1[3]) * g1[3]);
;                 *(u32x4*)rowp = w;
;             }
.LBB0_447:
	v_and_b32_e32 v149, 63, v163
	v_and_b32_e32 v150, 3, v149
	v_lshrrev_b32_e32 v151, 2, v149
	v_lshl_add_u32 v149, v150, 4, v151
	v_lshlrev_b32_e32 v149, 2, v149
	v_and_b32_e32 v148, 64, v142
	v_add_u32_e32 v148, v148, v151
	v_lshl_add_u32 v148, s62, 8, v148
	v_and_b32_e32 v140, 0x60, v146
	v_lshl_add_u32 v140, v150, 3, v140
	v_lshl_add_u32 v140, s63, 7, v140
	v_lshlrev_b32_e32 v140, 1, v140
	v_mad_u32_u24 v148, v148, s39, v140
	v_mul_f32_e32 v188, s46, v124
	v_mul_f32_e32 v189, s46, v125
	v_mul_f32_e32 v190, s46, v126
	v_mul_f32_e32 v191, s46, v127
	v_mul_f32_e32 v192, s46, v116
	v_mul_f32_e32 v193, s46, v117
	v_mul_f32_e32 v194, s46, v118
	v_mul_f32_e32 v195, s46, v119
	v_mul_f32_e32 v196, s46, v108
	v_mul_f32_e32 v197, s46, v109
	v_mul_f32_e32 v198, s46, v110
	v_mul_f32_e32 v199, s46, v111
	v_mul_f32_e32 v200, s46, v100
	v_mul_f32_e32 v201, s46, v101
	v_mul_f32_e32 v202, s46, v102
	v_mul_f32_e32 v203, s46, v103
	v_exp_f32_e32 v188, v188
	v_exp_f32_e32 v189, v189
	v_exp_f32_e32 v190, v190
	v_exp_f32_e32 v191, v191
	v_exp_f32_e32 v192, v192
	v_exp_f32_e32 v193, v193
	v_exp_f32_e32 v194, v194
	v_exp_f32_e32 v195, v195
	v_exp_f32_e32 v196, v196
	v_exp_f32_e32 v197, v197
	v_exp_f32_e32 v198, v198
	v_exp_f32_e32 v199, v199
	v_exp_f32_e32 v200, v200
	v_exp_f32_e32 v201, v201
	v_exp_f32_e32 v202, v202
	v_exp_f32_e32 v203, v203
	v_add_f32_e32 v188, 1.0, v188
	v_add_f32_e32 v189, 1.0, v189
	v_add_f32_e32 v190, 1.0, v190
	v_add_f32_e32 v191, 1.0, v191
	v_add_f32_e32 v192, 1.0, v192
	v_add_f32_e32 v193, 1.0, v193
	v_add_f32_e32 v194, 1.0, v194
	v_add_f32_e32 v195, 1.0, v195
	v_add_f32_e32 v196, 1.0, v196
	v_add_f32_e32 v197, 1.0, v197
	v_add_f32_e32 v198, 1.0, v198
	v_add_f32_e32 v199, 1.0, v199
	v_add_f32_e32 v200, 1.0, v200
	v_add_f32_e32 v201, 1.0, v201
	v_add_f32_e32 v202, 1.0, v202
	v_add_f32_e32 v203, 1.0, v203
	v_rcp_f32_e32 v188, v188
	v_rcp_f32_e32 v189, v189
	v_rcp_f32_e32 v190, v190
	v_rcp_f32_e32 v191, v191
	v_rcp_f32_e32 v192, v192
	v_rcp_f32_e32 v193, v193
	v_rcp_f32_e32 v194, v194
	v_rcp_f32_e32 v195, v195
	v_rcp_f32_e32 v196, v196
	v_rcp_f32_e32 v197, v197
	v_rcp_f32_e32 v198, v198
	v_rcp_f32_e32 v199, v199
	v_rcp_f32_e32 v200, v200
	v_rcp_f32_e32 v201, v201
	v_rcp_f32_e32 v202, v202
	v_rcp_f32_e32 v203, v203
	v_mul_f32_e32 v188, v124, v188
	v_mul_f32_e32 v189, v125, v189
	v_mul_f32_e32 v190, v126, v190
	v_mul_f32_e32 v191, v127, v191
	v_mul_f32_e32 v192, v116, v192
	v_mul_f32_e32 v193, v117, v193
	v_mul_f32_e32 v194, v118, v194
	v_mul_f32_e32 v195, v119, v195
	v_mul_f32_e32 v196, v108, v196
	v_mul_f32_e32 v197, v109, v197
	v_mul_f32_e32 v198, v110, v198
	v_mul_f32_e32 v199, v111, v199
	v_mul_f32_e32 v200, v100, v200
	v_mul_f32_e32 v201, v101, v201
	v_mul_f32_e32 v202, v102, v202
	v_mul_f32_e32 v203, v103, v203
	v_mul_f32_e32 v188, v188, v120
	v_mul_f32_e32 v189, v189, v121
	v_mul_f32_e32 v190, v190, v122
	v_mul_f32_e32 v191, v191, v123
	v_mul_f32_e32 v192, v192, v112
	v_mul_f32_e32 v193, v193, v113
	v_mul_f32_e32 v194, v194, v114
	v_mul_f32_e32 v195, v195, v115
	v_mul_f32_e32 v196, v196, v104
	v_mul_f32_e32 v197, v197, v105
	v_mul_f32_e32 v198, v198, v106
	v_mul_f32_e32 v199, v199, v107
	v_mul_f32_e32 v200, v200, v96
	v_mul_f32_e32 v201, v201, v97
	v_mul_f32_e32 v202, v202, v98
	v_mul_f32_e32 v203, v203, v99
	v_cvt_pk_bf16_f32 v204, v188, v189
	v_cvt_pk_bf16_f32 v205, v190, v191
	v_cvt_pk_bf16_f32 v206, v192, v193
	v_cvt_pk_bf16_f32 v207, v194, v195
	v_cvt_pk_bf16_f32 v208, v196, v197
	v_cvt_pk_bf16_f32 v209, v198, v199
	v_cvt_pk_bf16_f32 v210, v200, v201
	v_cvt_pk_bf16_f32 v211, v202, v203
	ds_bpermute_b32 v212, v149, v204
	ds_bpermute_b32 v213, v149, v205
	ds_bpermute_b32 v214, v149, v206
	ds_bpermute_b32 v215, v149, v207
	ds_bpermute_b32 v216, v149, v208
	ds_bpermute_b32 v217, v149, v209
	ds_bpermute_b32 v218, v149, v210
	ds_bpermute_b32 v219, v149, v211
	v_mul_f32_e32 v188, s46, v92
	v_mul_f32_e32 v189, s46, v93
	v_mul_f32_e32 v190, s46, v94
	v_mul_f32_e32 v191, s46, v95
	v_mul_f32_e32 v192, s46, v84
	v_mul_f32_e32 v193, s46, v85
	v_mul_f32_e32 v194, s46, v86
	v_mul_f32_e32 v195, s46, v87
	v_mul_f32_e32 v196, s46, v76
	v_mul_f32_e32 v197, s46, v77
	v_mul_f32_e32 v198, s46, v78
	v_mul_f32_e32 v199, s46, v79
	v_mul_f32_e32 v200, s46, v68
	v_mul_f32_e32 v201, s46, v69
	v_mul_f32_e32 v202, s46, v70
	v_mul_f32_e32 v203, s46, v71
	v_exp_f32_e32 v188, v188
	v_exp_f32_e32 v189, v189
	v_exp_f32_e32 v190, v190
	v_exp_f32_e32 v191, v191
	v_exp_f32_e32 v192, v192
	v_exp_f32_e32 v193, v193
	v_exp_f32_e32 v194, v194
	v_exp_f32_e32 v195, v195
	v_exp_f32_e32 v196, v196
	v_exp_f32_e32 v197, v197
	v_exp_f32_e32 v198, v198
	v_exp_f32_e32 v199, v199
	v_exp_f32_e32 v200, v200
	v_exp_f32_e32 v201, v201
	v_exp_f32_e32 v202, v202
	v_exp_f32_e32 v203, v203
	v_add_f32_e32 v188, 1.0, v188
	v_add_f32_e32 v189, 1.0, v189
	v_add_f32_e32 v190, 1.0, v190
	v_add_f32_e32 v191, 1.0, v191
	v_add_f32_e32 v192, 1.0, v192
	v_add_f32_e32 v193, 1.0, v193
	v_add_f32_e32 v194, 1.0, v194
	v_add_f32_e32 v195, 1.0, v195
	v_add_f32_e32 v196, 1.0, v196
	v_add_f32_e32 v197, 1.0, v197
	v_add_f32_e32 v198, 1.0, v198
	v_add_f32_e32 v199, 1.0, v199
	v_add_f32_e32 v200, 1.0, v200
	v_add_f32_e32 v201, 1.0, v201
	v_add_f32_e32 v202, 1.0, v202
	v_add_f32_e32 v203, 1.0, v203
	v_rcp_f32_e32 v188, v188
	v_rcp_f32_e32 v189, v189
	v_rcp_f32_e32 v190, v190
	v_rcp_f32_e32 v191, v191
	v_rcp_f32_e32 v192, v192
	v_rcp_f32_e32 v193, v193
	v_rcp_f32_e32 v194, v194
	v_rcp_f32_e32 v195, v195
	v_rcp_f32_e32 v196, v196
	v_rcp_f32_e32 v197, v197
	v_rcp_f32_e32 v198, v198
	v_rcp_f32_e32 v199, v199
	v_rcp_f32_e32 v200, v200
	v_rcp_f32_e32 v201, v201
	v_rcp_f32_e32 v202, v202
	v_rcp_f32_e32 v203, v203
	v_mul_f32_e32 v188, v92, v188
	v_mul_f32_e32 v189, v93, v189
	v_mul_f32_e32 v190, v94, v190
	v_mul_f32_e32 v191, v95, v191
	v_mul_f32_e32 v192, v84, v192
	v_mul_f32_e32 v193, v85, v193
	v_mul_f32_e32 v194, v86, v194
	v_mul_f32_e32 v195, v87, v195
	v_mul_f32_e32 v196, v76, v196
	v_mul_f32_e32 v197, v77, v197
	v_mul_f32_e32 v198, v78, v198
	v_mul_f32_e32 v199, v79, v199
	v_mul_f32_e32 v200, v68, v200
	v_mul_f32_e32 v201, v69, v201
	v_mul_f32_e32 v202, v70, v202
	v_mul_f32_e32 v203, v71, v203
	v_mul_f32_e32 v188, v188, v88
	v_mul_f32_e32 v189, v189, v89
	v_mul_f32_e32 v190, v190, v90
	v_mul_f32_e32 v191, v191, v91
	v_mul_f32_e32 v192, v192, v80
	v_mul_f32_e32 v193, v193, v81
	v_mul_f32_e32 v194, v194, v82
	v_mul_f32_e32 v195, v195, v83
	v_mul_f32_e32 v196, v196, v72
	v_mul_f32_e32 v197, v197, v73
	v_mul_f32_e32 v198, v198, v74
	v_mul_f32_e32 v199, v199, v75
	v_mul_f32_e32 v200, v200, v64
	v_mul_f32_e32 v201, v201, v65
	v_mul_f32_e32 v202, v202, v66
	v_mul_f32_e32 v203, v203, v67
	s_waitcnt lgkmcnt(0)
; __device__ __forceinline__ unsigned pk2(float lo, float hi) { return pg8::cvt_pk_bf16(lo, hi); }
; __device__ __forceinline__ float siluf_(float x) { return x * sigmoidf_(x); }
;     __device__ __forceinline__ void operator()(const f32x4 (&acc)[2][2][4][2], const pg8::Unit& u, int wr, int wc, int fr, int fq) const {
;     ...
;                 bf16_t* rowp = O + (size_t)(row0 + ai * 128 + m * 16) * ldc + col0;
;                 const f32x4 a0 = acc[ai][0][m][0], a1 = acc[ai][0][m][1], g0 = acc[ai][1][m][0], g1 = acc[ai][1][m][1];
;                 u32x4 w;
;                 w.x = pk2(siluf_(a0[0]) * g0[0], siluf_(a0[1]) * g0[1]); w.y = pk2(siluf_(a0[2]) * g0[2], siluf_(a0[3]) * g0[3]);
;                 w.z = pk2(siluf_(a1[0]) * g1[0], siluf_(a1[1]) * g1[1]); w.w = pk2(siluf_(a1[2]) * g1[2], siluf_(a1[3]) * g1[3]);
;                 *(u32x4*)rowp = w;
	global_store_dwordx4 v148, v[212:215], s[58:59]
	v_add_u32_e32 v148, 0x16000, v148
	global_store_dwordx4 v148, v[216:219], s[58:59]
	v_add_u32_e32 v148, 0x16000, v148
	v_cvt_pk_bf16_f32 v204, v188, v189
	v_cvt_pk_bf16_f32 v205, v190, v191
	v_cvt_pk_bf16_f32 v206, v192, v193
	v_cvt_pk_bf16_f32 v207, v194, v195
	v_cvt_pk_bf16_f32 v208, v196, v197
	v_cvt_pk_bf16_f32 v209, v198, v199
	v_cvt_pk_bf16_f32 v210, v200, v201
	v_cvt_pk_bf16_f32 v211, v202, v203
	ds_bpermute_b32 v212, v149, v204
	ds_bpermute_b32 v213, v149, v205
	ds_bpermute_b32 v214, v149, v206
	ds_bpermute_b32 v215, v149, v207
	ds_bpermute_b32 v216, v149, v208
	ds_bpermute_b32 v217, v149, v209
	ds_bpermute_b32 v218, v149, v210
	ds_bpermute_b32 v219, v149, v211
	v_mul_f32_e32 v188, s46, v60
	v_mul_f32_e32 v189, s46, v61
	v_mul_f32_e32 v190, s46, v62
	v_mul_f32_e32 v191, s46, v63
	v_mul_f32_e32 v192, s46, v52
	v_mul_f32_e32 v193, s46, v53
	v_mul_f32_e32 v194, s46, v54
	v_mul_f32_e32 v195, s46, v55
	v_mul_f32_e32 v196, s46, v44
	v_mul_f32_e32 v197, s46, v45
	v_mul_f32_e32 v198, s46, v46
	v_mul_f32_e32 v199, s46, v47
	v_mul_f32_e32 v200, s46, v36
	v_mul_f32_e32 v201, s46, v37
	v_mul_f32_e32 v202, s46, v38
	v_mul_f32_e32 v203, s46, v39
	v_exp_f32_e32 v188, v188
	v_exp_f32_e32 v189, v189
	v_exp_f32_e32 v190, v190
	v_exp_f32_e32 v191, v191
	v_exp_f32_e32 v192, v192
	v_exp_f32_e32 v193, v193
	v_exp_f32_e32 v194, v194
	v_exp_f32_e32 v195, v195
	v_exp_f32_e32 v196, v196
	v_exp_f32_e32 v197, v197
	v_exp_f32_e32 v198, v198
	v_exp_f32_e32 v199, v199
	v_exp_f32_e32 v200, v200
	v_exp_f32_e32 v201, v201
	v_exp_f32_e32 v202, v202
	v_exp_f32_e32 v203, v203
	v_add_f32_e32 v188, 1.0, v188
	v_add_f32_e32 v189, 1.0, v189
	v_add_f32_e32 v190, 1.0, v190
	v_add_f32_e32 v191, 1.0, v191
	v_add_f32_e32 v192, 1.0, v192
	v_add_f32_e32 v193, 1.0, v193
	v_add_f32_e32 v194, 1.0, v194
	v_add_f32_e32 v195, 1.0, v195
	v_add_f32_e32 v196, 1.0, v196
	v_add_f32_e32 v197, 1.0, v197
	v_add_f32_e32 v198, 1.0, v198
	v_add_f32_e32 v199, 1.0, v199
	v_add_f32_e32 v200, 1.0, v200
	v_add_f32_e32 v201, 1.0, v201
	v_add_f32_e32 v202, 1.0, v202
	v_add_f32_e32 v203, 1.0, v203
	v_rcp_f32_e32 v188, v188
	v_rcp_f32_e32 v189, v189
	v_rcp_f32_e32 v190, v190
	v_rcp_f32_e32 v191, v191
	v_rcp_f32_e32 v192, v192
	v_rcp_f32_e32 v193, v193
	v_rcp_f32_e32 v194, v194
	v_rcp_f32_e32 v195, v195
	v_rcp_f32_e32 v196, v196
	v_rcp_f32_e32 v197, v197
	v_rcp_f32_e32 v198, v198
	v_rcp_f32_e32 v199, v199
	v_rcp_f32_e32 v200, v200
	v_rcp_f32_e32 v201, v201
	v_rcp_f32_e32 v202, v202
	v_rcp_f32_e32 v203, v203
	v_mul_f32_e32 v188, v60, v188
	v_mul_f32_e32 v189, v61, v189
	v_mul_f32_e32 v190, v62, v190
	v_mul_f32_e32 v191, v63, v191
	v_mul_f32_e32 v192, v52, v192
	v_mul_f32_e32 v193, v53, v193
	v_mul_f32_e32 v194, v54, v194
	v_mul_f32_e32 v195, v55, v195
	v_mul_f32_e32 v196, v44, v196
	v_mul_f32_e32 v197, v45, v197
	v_mul_f32_e32 v198, v46, v198
	v_mul_f32_e32 v199, v47, v199
	v_mul_f32_e32 v200, v36, v200
	v_mul_f32_e32 v201, v37, v201
	v_mul_f32_e32 v202, v38, v202
	v_mul_f32_e32 v203, v39, v203
	v_mul_f32_e32 v188, v188, v56
	v_mul_f32_e32 v189, v189, v57
	v_mul_f32_e32 v190, v190, v58
	v_mul_f32_e32 v191, v191, v59
	v_mul_f32_e32 v192, v192, v48
	v_mul_f32_e32 v193, v193, v49
	v_mul_f32_e32 v194, v194, v50
	v_mul_f32_e32 v195, v195, v51
	v_mul_f32_e32 v196, v196, v40
	v_mul_f32_e32 v197, v197, v41
	v_mul_f32_e32 v198, v198, v42
	v_mul_f32_e32 v199, v199, v43
	v_mul_f32_e32 v200, v200, v32
	v_mul_f32_e32 v201, v201, v33
	v_mul_f32_e32 v202, v202, v34
	v_mul_f32_e32 v203, v203, v35
	s_waitcnt lgkmcnt(0)
; __device__ __forceinline__ unsigned pk2(float lo, float hi) { return pg8::cvt_pk_bf16(lo, hi); }
; __device__ __forceinline__ float siluf_(float x) { return x * sigmoidf_(x); }
;     __device__ __forceinline__ void operator()(const f32x4 (&acc)[2][2][4][2], const pg8::Unit& u, int wr, int wc, int fr, int fq) const {
;     ...
;                 bf16_t* rowp = O + (size_t)(row0 + ai * 128 + m * 16) * ldc + col0;
;                 const f32x4 a0 = acc[ai][0][m][0], a1 = acc[ai][0][m][1], g0 = acc[ai][1][m][0], g1 = acc[ai][1][m][1];
;                 u32x4 w;
;                 w.x = pk2(siluf_(a0[0]) * g0[0], siluf_(a0[1]) * g0[1]); w.y = pk2(siluf_(a0[2]) * g0[2], siluf_(a0[3]) * g0[3]);
;                 w.z = pk2(siluf_(a1[0]) * g1[0], siluf_(a1[1]) * g1[1]); w.w = pk2(siluf_(a1[2]) * g1[2], siluf_(a1[3]) * g1[3]);
;                 *(u32x4*)rowp = w;
	global_store_dwordx4 v148, v[212:215], s[58:59]
	v_add_u32_e32 v148, 0x16000, v148
	global_store_dwordx4 v148, v[216:219], s[58:59]
	v_add_u32_e32 v148, 0x6e000, v148
	v_cvt_pk_bf16_f32 v204, v188, v189
	v_cvt_pk_bf16_f32 v205, v190, v191
	v_cvt_pk_bf16_f32 v206, v192, v193
	v_cvt_pk_bf16_f32 v207, v194, v195
	v_cvt_pk_bf16_f32 v208, v196, v197
	v_cvt_pk_bf16_f32 v209, v198, v199
	v_cvt_pk_bf16_f32 v210, v200, v201
	v_cvt_pk_bf16_f32 v211, v202, v203
	ds_bpermute_b32 v212, v149, v204
	ds_bpermute_b32 v213, v149, v205
	ds_bpermute_b32 v214, v149, v206
	ds_bpermute_b32 v215, v149, v207
	ds_bpermute_b32 v216, v149, v208
	ds_bpermute_b32 v217, v149, v209
	ds_bpermute_b32 v218, v149, v210
	ds_bpermute_b32 v219, v149, v211
	v_mul_f32_e32 v188, s46, v28
	v_mul_f32_e32 v189, s46, v29
	v_mul_f32_e32 v190, s46, v30
	v_mul_f32_e32 v191, s46, v31
	v_mul_f32_e32 v192, s46, v20
	v_mul_f32_e32 v193, s46, v21
	v_mul_f32_e32 v194, s46, v22
	v_mul_f32_e32 v195, s46, v23
	v_mul_f32_e32 v196, s46, v12
	v_mul_f32_e32 v197, s46, v13
	v_mul_f32_e32 v198, s46, v14
	v_mul_f32_e32 v199, s46, v15
	v_mul_f32_e32 v200, s46, v4
	v_mul_f32_e32 v201, s46, v5
	v_mul_f32_e32 v202, s46, v6
	v_mul_f32_e32 v203, s46, v7
	v_exp_f32_e32 v188, v188
	v_exp_f32_e32 v189, v189
	v_exp_f32_e32 v190, v190
	v_exp_f32_e32 v191, v191
	v_exp_f32_e32 v192, v192
	v_exp_f32_e32 v193, v193
	v_exp_f32_e32 v194, v194
	v_exp_f32_e32 v195, v195
	v_exp_f32_e32 v196, v196
	v_exp_f32_e32 v197, v197
	v_exp_f32_e32 v198, v198
	v_exp_f32_e32 v199, v199
	v_exp_f32_e32 v200, v200
	v_exp_f32_e32 v201, v201
	v_exp_f32_e32 v202, v202
	v_exp_f32_e32 v203, v203
	v_add_f32_e32 v188, 1.0, v188
	v_add_f32_e32 v189, 1.0, v189
	v_add_f32_e32 v190, 1.0, v190
	v_add_f32_e32 v191, 1.0, v191
	v_add_f32_e32 v192, 1.0, v192
	v_add_f32_e32 v193, 1.0, v193
	v_add_f32_e32 v194, 1.0, v194
	v_add_f32_e32 v195, 1.0, v195
	v_add_f32_e32 v196, 1.0, v196
	v_add_f32_e32 v197, 1.0, v197
	v_add_f32_e32 v198, 1.0, v198
	v_add_f32_e32 v199, 1.0, v199
	v_add_f32_e32 v200, 1.0, v200
	v_add_f32_e32 v201, 1.0, v201
	v_add_f32_e32 v202, 1.0, v202
	v_add_f32_e32 v203, 1.0, v203
	v_rcp_f32_e32 v188, v188
	v_rcp_f32_e32 v189, v189
	v_rcp_f32_e32 v190, v190
	v_rcp_f32_e32 v191, v191
	v_rcp_f32_e32 v192, v192
	v_rcp_f32_e32 v193, v193
	v_rcp_f32_e32 v194, v194
	v_rcp_f32_e32 v195, v195
	v_rcp_f32_e32 v196, v196
	v_rcp_f32_e32 v197, v197
	v_rcp_f32_e32 v198, v198
	v_rcp_f32_e32 v199, v199
	v_rcp_f32_e32 v200, v200
	v_rcp_f32_e32 v201, v201
	v_rcp_f32_e32 v202, v202
	v_rcp_f32_e32 v203, v203
	v_mul_f32_e32 v188, v28, v188
	v_mul_f32_e32 v189, v29, v189
	v_mul_f32_e32 v190, v30, v190
	v_mul_f32_e32 v191, v31, v191
	v_mul_f32_e32 v192, v20, v192
	v_mul_f32_e32 v193, v21, v193
	v_mul_f32_e32 v194, v22, v194
	v_mul_f32_e32 v195, v23, v195
	v_mul_f32_e32 v196, v12, v196
	v_mul_f32_e32 v197, v13, v197
	v_mul_f32_e32 v198, v14, v198
	v_mul_f32_e32 v199, v15, v199
	v_mul_f32_e32 v200, v4, v200
	v_mul_f32_e32 v201, v5, v201
	v_mul_f32_e32 v202, v6, v202
	v_mul_f32_e32 v203, v7, v203
	v_mul_f32_e32 v188, v188, v24
	v_mul_f32_e32 v189, v189, v25
	v_mul_f32_e32 v190, v190, v26
	v_mul_f32_e32 v191, v191, v27
	v_mul_f32_e32 v192, v192, v16
	v_mul_f32_e32 v193, v193, v17
	v_mul_f32_e32 v194, v194, v18
	v_mul_f32_e32 v195, v195, v19
	v_mul_f32_e32 v196, v196, v8
	v_mul_f32_e32 v197, v197, v9
	v_mul_f32_e32 v198, v198, v10
	v_mul_f32_e32 v199, v199, v11
	v_mul_f32_e32 v200, v200, v0
	v_mul_f32_e32 v201, v201, v1
	v_mul_f32_e32 v202, v202, v2
	v_mul_f32_e32 v203, v203, v3
	s_waitcnt lgkmcnt(0)
	global_store_dwordx4 v148, v[212:215], s[58:59]
	v_add_u32_e32 v148, 0x16000, v148
	global_store_dwordx4 v148, v[216:219], s[58:59]
	v_add_u32_e32 v148, 0x16000, v148
	v_cvt_pk_bf16_f32 v204, v188, v189
	v_cvt_pk_bf16_f32 v205, v190, v191
	v_cvt_pk_bf16_f32 v206, v192, v193
	v_cvt_pk_bf16_f32 v207, v194, v195
	v_cvt_pk_bf16_f32 v208, v196, v197
	v_cvt_pk_bf16_f32 v209, v198, v199
	v_cvt_pk_bf16_f32 v210, v200, v201
	v_cvt_pk_bf16_f32 v211, v202, v203
	ds_bpermute_b32 v212, v149, v204
	ds_bpermute_b32 v213, v149, v205
	ds_bpermute_b32 v214, v149, v206
	ds_bpermute_b32 v215, v149, v207
	ds_bpermute_b32 v216, v149, v208
	ds_bpermute_b32 v217, v149, v209
	ds_bpermute_b32 v218, v149, v210
	ds_bpermute_b32 v219, v149, v211
	s_waitcnt lgkmcnt(0)
	global_store_dwordx4 v148, v[212:215], s[58:59]
	v_add_u32_e32 v148, 0x16000, v148
	global_store_dwordx4 v148, v[216:219], s[58:59]
	s_mov_b64 s[62:63], -1
	s_andn2_b64 vcc, exec, s[8:9]
	s_cbranch_vccnz .LBB0_440
	s_andn2_b64 vcc, exec, s[10:11]
	s_cbranch_vccnz .LBB0_439
	s_barrier
	s_branch .LBB0_439

; #define FB_LD(p) __hip_atomic_load((p), __ATOMIC_RELAXED, __HIP_MEMORY_SCOPE_AGENT)
; #define FB_ST(p, v) __hip_atomic_store((p), (v), __ATOMIC_RELAXED, __HIP_MEMORY_SCOPE_AGENT)
; __device__ __forceinline__ void flag_barrier(unsigned* base, unsigned gen) {
;     ...
;         if (c == 0) {
;             unsigned sp = 0;
;             for (;;) {
;                 unsigned ok = 1u;
;                 for (int m = lane; m < G; m += 64) ok &= (unsigned)(FB_LD(base + 64 * (1 + m)) >= gen);
;                 if (__all((int)ok)) break;
;                 __builtin_amdgcn_s_sleep(1); if (++sp > (1u << 22)) break;
;             }
;             if (lane == 0) FB_ST(base, gen);
;         }
.LBB0_504:
	s_mov_b64 s[20:21], -1
	s_and_saveexec_b64 s[14:15], s[8:9]
	s_cbranch_execz .LBB0_508
	s_cmpk_lg_i32 s5, 0x100
	s_cbranch_scc1 .Lbar_generic
	v_lshlrev_b32_e32 v0, 8, v163
	global_load_dword v1, v0, s[12:13] offset:256 sc1
	v_add_u32_e32 v3, 0x4000, v0
	global_load_dword v4, v3, s[12:13] offset:256 sc1
	v_add_u32_e32 v3, 0x8000, v0
	global_load_dword v5, v3, s[12:13] offset:256 sc1
	v_add_u32_e32 v3, 0xc000, v0
	global_load_dword v6, v3, s[12:13] offset:256 sc1
	s_waitcnt vmcnt(0)
	v_min_u32_e32 v1, v1, v4
	v_min_u32_e32 v5, v5, v6
	v_min_u32_e32 v1, v1, v5
	v_cmp_le_u32_e32 vcc, s4, v1
	s_orn2_b64 s[20:21], vcc, exec
	s_branch .LBB0_508
.Lbar_generic:
	v_mov_b32_e32 v2, 1
	s_mov_b64 s[20:21], 0
	v_lshlrev_b32_e32 v0, 6, v163
	v_mov_b32_e32 v3, v163
